# GU tail: step 0 goes to three whole bid%8 groups (5,6,7) blindly, steps 1-2 to the three measured-fastest groups
# baseline (speedup 1.0000x reference)
.LBB0_840:
	s_add_u32 s6, s6, 0xac00000
	s_addc_u32 s7, s7, 0
	v_and_b32_e32 v17, 15, v16
	v_lshrrev_b32_e32 v18, 1, v16
	s_lshl_b32 s2, s2, 5
	v_and_b32_e32 v18, 24, v18
	v_lshlrev_b32_e32 v19, 6, v17
	v_lshlrev_b32_e32 v16, 2, v16
	s_and_b32 s22, s2, 0x60
	s_add_i32 m0, s46, 0x18000
	v_lshl_add_u64 v[8:9], v[8:9], 0, s[70:71]
	v_lshl_or_b32 v19, v18, 1, v19
	v_and_b32_e32 v16, 32, v16
	v_lshl_or_b32 v144, s3, 6, v17
	s_lshl_b32 s3, s3, 13
	s_lshl_b32 s2, s22, 7
	s_waitcnt vmcnt(2)
	s_barrier
	global_load_lds_dwordx4 v[8:9], off
	v_lshl_add_u64 v[6:7], v[6:7], 0, s[70:71]
	s_add_i32 m0, s46, 0x1a000
	s_add_i32 s50, s46, 0x8000
	s_add_i32 s51, s46, 0xa000
	v_bitop3_b32 v145, s2, v19, v16 bitop3:0xf6
	global_load_lds_dwordx4 v[6:7], off
	v_lshl_add_u64 v[2:3], v[2:3], 0, s[70:71]
	s_mov_b32 m0, s50
	s_add_u32 s2, s38, 0x40080
	v_bitop3_b32 v17, v19, s3, v16 bitop3:0xde
	global_load_lds_dwordx4 v[2:3], off
	v_lshl_add_u64 v[2:3], v[4:5], 0, s[70:71]
	s_mov_b32 m0, s51
	s_addc_u32 s3, s39, 0
	global_load_lds_dwordx4 v[2:3], off
	s_add_i32 m0, s46, 0x1c000
	v_lshl_add_u64 v[2:3], s[2:3], 0, v[0:1]
	global_load_lds_dwordx4 v[2:3], off
	v_lshl_add_u64 v[2:3], s[2:3], 0, v[134:135]
	s_add_i32 m0, s46, 0x1e000
	s_cmpk_lt_u32 s9, 0x100
	global_load_lds_dwordx4 v[2:3], off
	v_lshlrev_b32_e32 v2, 14, v10
	v_and_b32_e32 v2, 0xffff8000, v2
	v_lshl_add_u32 v2, v11, 11, v2
	v_and_b32_e32 v3, 1, v10
	v_lshl_or_b32 v2, v3, 6, v2
	v_lshl_add_u32 v136, v12, 1, v2
	v_lshlrev_b32_e32 v2, 14, v13
	v_and_b32_e32 v2, 0xffff8000, v2
	s_waitcnt vmcnt(6)
	v_lshl_add_u32 v2, v14, 11, v2
	v_and_b32_e32 v3, 1, v13
	v_lshl_or_b32 v2, v3, 6, v2
	s_cselect_b64 s[14:15], -1, 0
	v_or_b32_e32 v146, s22, v18
	v_mov_b32_e32 v137, v1
	v_lshl_add_u32 v138, v15, 1, v2
	v_mov_b32_e32 v139, v1
	s_mov_b32 s52, 0
	v_add_u32_e32 v147, 0, v17
	s_barrier
	s_mov_b32 s100, 0x10000
	s_cmpk_lg_u32 s33, 0x100
	s_cbranch_scc1 .Lslot_done
	s_add_i32 s101, s8, 3
	s_and_b32 s101, s101, 7
	s_cmp_eq_u32 s65, 0
	s_cbranch_scc1 .Lslot_have
	s_load_dwordx2 s[98:99], s[0:1], 0x128
	s_and_b32 s101, s8, 7
	s_lshl_b32 s101, s101, 8
	s_waitcnt lgkmcnt(0)
	s_add_u32 s98, s98, s101
	s_addc_u32 s99, s99, 0
	s_add_u32 s98, s98, 0x302400
	s_addc_u32 s99, s99, 0
	global_load_dword v2, v1, s[98:99] sc1
	s_waitcnt vmcnt(0)
	v_readfirstlane_b32 s101, v2
	s_nop 3
.Lslot_have:
	s_cmp_lt_u32 s101, 3
	s_cbranch_scc0 .Lslot_done
	s_lshl_b32 s101, s101, 5
	s_lshr_b32 s100, s8, 3
	s_add_i32 s100, s100, s101
